# speedup vs baseline: 1.0379x; 1.0012x over previous
; template <int MODE> ...
;     ...
;           mx = fmaxf(mx, __shfl_xor(mx, 32));
;           if (__any(mx > m_run + 8.f)) {
;             const float m_new = fmaxf(m_run, mx);
;             const float alpha = __builtin_amdgcn_exp2f(m_run - m_new);
;             l_run *= alpha;
;             m_run = m_new;
; #pragma unroll
;             for (int mb = 0; mb < 4; ++mb)
; #pragma unroll
;               for (int i = 0; i < 16; ++i) O[mb][i] *= alpha;
;           }
.LBB0_357:
	s_or_b64 exec, exec, s[10:11]
	v_mov_b32_e32 v180, v0
	s_nop 1
	v_permlane32_swap_b32 v180, v0
	s_nop 1
	v_max_f32_e32 v0, v0, v180
	v_add_f32_e32 v180, 0x41000000, v217
	v_cmp_gt_f32_e32 vcc, v0, v180
	s_cbranch_vccz .LBB0_359
	v_max_f32_e32 v0, v0, v0
	v_max_f32_e32 v180, v217, v217
	v_max_f32_e32 v180, v180, v0
	v_sub_f32_e32 v0, v217, v180
	v_exp_f32_e32 v0, v0
	v_mov_b32_e32 v217, v180
	v_pk_mul_f32 v[94:95], v[94:95], v[0:1] op_sel_hi:[1,0]
	v_pk_mul_f32 v[92:93], v[92:93], v[0:1] op_sel_hi:[1,0]
	v_pk_mul_f32 v[90:91], v[90:91], v[0:1] op_sel_hi:[1,0]
	v_pk_mul_f32 v[88:89], v[88:89], v[0:1] op_sel_hi:[1,0]
	v_pk_mul_f32 v[86:87], v[86:87], v[0:1] op_sel_hi:[1,0]
	v_pk_mul_f32 v[84:85], v[84:85], v[0:1] op_sel_hi:[1,0]
	v_pk_mul_f32 v[82:83], v[82:83], v[0:1] op_sel_hi:[1,0]
	v_pk_mul_f32 v[80:81], v[80:81], v[0:1] op_sel_hi:[1,0]
	v_pk_mul_f32 v[78:79], v[78:79], v[0:1] op_sel_hi:[1,0]
	v_pk_mul_f32 v[76:77], v[76:77], v[0:1] op_sel_hi:[1,0]
	v_pk_mul_f32 v[74:75], v[74:75], v[0:1] op_sel_hi:[1,0]
	v_pk_mul_f32 v[72:73], v[72:73], v[0:1] op_sel_hi:[1,0]
	v_pk_mul_f32 v[70:71], v[70:71], v[0:1] op_sel_hi:[1,0]
	v_pk_mul_f32 v[68:69], v[68:69], v[0:1] op_sel_hi:[1,0]
	v_pk_mul_f32 v[66:67], v[66:67], v[0:1] op_sel_hi:[1,0]
	v_pk_mul_f32 v[64:65], v[64:65], v[0:1] op_sel_hi:[1,0]
	v_pk_mul_f32 v[62:63], v[62:63], v[0:1] op_sel_hi:[1,0]
	v_pk_mul_f32 v[60:61], v[60:61], v[0:1] op_sel_hi:[1,0]
	v_pk_mul_f32 v[58:59], v[58:59], v[0:1] op_sel_hi:[1,0]
	v_pk_mul_f32 v[56:57], v[56:57], v[0:1] op_sel_hi:[1,0]
	v_pk_mul_f32 v[54:55], v[54:55], v[0:1] op_sel_hi:[1,0]
	v_pk_mul_f32 v[52:53], v[52:53], v[0:1] op_sel_hi:[1,0]
	v_pk_mul_f32 v[50:51], v[50:51], v[0:1] op_sel_hi:[1,0]
	v_pk_mul_f32 v[48:49], v[48:49], v[0:1] op_sel_hi:[1,0]
	v_pk_mul_f32 v[46:47], v[46:47], v[0:1] op_sel_hi:[1,0]
	v_pk_mul_f32 v[44:45], v[44:45], v[0:1] op_sel_hi:[1,0]
	v_pk_mul_f32 v[42:43], v[42:43], v[0:1] op_sel_hi:[1,0]
	v_pk_mul_f32 v[40:41], v[40:41], v[0:1] op_sel_hi:[1,0]
	v_pk_mul_f32 v[38:39], v[38:39], v[0:1] op_sel_hi:[1,0]
	v_pk_mul_f32 v[36:37], v[36:37], v[0:1] op_sel_hi:[1,0]
	v_pk_mul_f32 v[34:35], v[34:35], v[0:1] op_sel_hi:[1,0]
	v_pk_mul_f32 v[32:33], v[32:33], v[0:1] op_sel_hi:[1,0]
	v_mul_f32_e32 v216, v216, v0

; template <int MODE> ...
;     ...
;           mx = fmaxf(mx, __shfl_xor(mx, 32));
;           if (__any(mx > m_run + 8.f)) {
;             const float m_new = fmaxf(m_run, mx);
;             const float alpha = __builtin_amdgcn_exp2f(m_run - m_new);
;             l_run *= alpha;
;             m_run = m_new;
; #pragma unroll
;             for (int mb = 0; mb < 4; ++mb)
; #pragma unroll
;               for (int i = 0; i < 16; ++i) O[mb][i] *= alpha;
;           }
.LBB0_371:
	s_or_b64 exec, exec, s[10:11]
	v_mov_b32_e32 v180, v0
	s_nop 1
	v_permlane32_swap_b32 v180, v0
	s_nop 1
	v_max_f32_e32 v0, v0, v180
	v_add_f32_e32 v180, 0x41000000, v217
	v_cmp_gt_f32_e32 vcc, v0, v180
	s_cbranch_vccz .LBB0_348
	v_max_f32_e32 v0, v0, v0
	v_max_f32_e32 v180, v217, v217
	v_max_f32_e32 v180, v180, v0
	v_sub_f32_e32 v0, v217, v180
	v_exp_f32_e32 v0, v0
	v_mov_b32_e32 v217, v180
	v_pk_mul_f32 v[94:95], v[94:95], v[0:1] op_sel_hi:[1,0]
	v_pk_mul_f32 v[92:93], v[92:93], v[0:1] op_sel_hi:[1,0]
	v_pk_mul_f32 v[90:91], v[90:91], v[0:1] op_sel_hi:[1,0]
	v_pk_mul_f32 v[88:89], v[88:89], v[0:1] op_sel_hi:[1,0]
	v_pk_mul_f32 v[86:87], v[86:87], v[0:1] op_sel_hi:[1,0]
	v_pk_mul_f32 v[84:85], v[84:85], v[0:1] op_sel_hi:[1,0]
	v_pk_mul_f32 v[82:83], v[82:83], v[0:1] op_sel_hi:[1,0]
	v_pk_mul_f32 v[80:81], v[80:81], v[0:1] op_sel_hi:[1,0]
	v_pk_mul_f32 v[78:79], v[78:79], v[0:1] op_sel_hi:[1,0]
	v_pk_mul_f32 v[76:77], v[76:77], v[0:1] op_sel_hi:[1,0]
	v_pk_mul_f32 v[74:75], v[74:75], v[0:1] op_sel_hi:[1,0]
	v_pk_mul_f32 v[72:73], v[72:73], v[0:1] op_sel_hi:[1,0]
	v_pk_mul_f32 v[70:71], v[70:71], v[0:1] op_sel_hi:[1,0]
	v_pk_mul_f32 v[68:69], v[68:69], v[0:1] op_sel_hi:[1,0]
	v_pk_mul_f32 v[66:67], v[66:67], v[0:1] op_sel_hi:[1,0]
	v_pk_mul_f32 v[64:65], v[64:65], v[0:1] op_sel_hi:[1,0]
	v_pk_mul_f32 v[62:63], v[62:63], v[0:1] op_sel_hi:[1,0]
	v_pk_mul_f32 v[60:61], v[60:61], v[0:1] op_sel_hi:[1,0]
	v_pk_mul_f32 v[58:59], v[58:59], v[0:1] op_sel_hi:[1,0]
	v_pk_mul_f32 v[56:57], v[56:57], v[0:1] op_sel_hi:[1,0]
	v_pk_mul_f32 v[54:55], v[54:55], v[0:1] op_sel_hi:[1,0]
	v_pk_mul_f32 v[52:53], v[52:53], v[0:1] op_sel_hi:[1,0]
	v_pk_mul_f32 v[50:51], v[50:51], v[0:1] op_sel_hi:[1,0]
	v_pk_mul_f32 v[48:49], v[48:49], v[0:1] op_sel_hi:[1,0]
	v_pk_mul_f32 v[46:47], v[46:47], v[0:1] op_sel_hi:[1,0]
	v_pk_mul_f32 v[44:45], v[44:45], v[0:1] op_sel_hi:[1,0]
	v_pk_mul_f32 v[42:43], v[42:43], v[0:1] op_sel_hi:[1,0]
	v_pk_mul_f32 v[40:41], v[40:41], v[0:1] op_sel_hi:[1,0]
	v_pk_mul_f32 v[38:39], v[38:39], v[0:1] op_sel_hi:[1,0]
	v_pk_mul_f32 v[36:37], v[36:37], v[0:1] op_sel_hi:[1,0]
	v_pk_mul_f32 v[34:35], v[34:35], v[0:1] op_sel_hi:[1,0]
	v_pk_mul_f32 v[32:33], v[32:33], v[0:1] op_sel_hi:[1,0]
	v_mul_f32_e32 v216, v216, v0
	s_branch .LBB0_348
